# combo11 + phase-0 row loop: all four f32 row loads issued together with counted vmcnt waits (one round trip per row instead of four)
# speedup vs baseline: 1.0038x; 1.0038x over previous
.LBB0_32:
	s_waitcnt lgkmcnt(0)
	global_load_dwordx4 v[12:15], v0, s[24:25] nt
	global_load_dwordx4 v[16:19], v0, s[24:25] offset:1024 nt
	global_load_dwordx4 v[20:23], v0, s[24:25] offset:2048 nt
	global_load_dwordx4 v[24:27], v0, s[24:25] offset:3072 nt
	s_lshl_b64 s[26:27], s[22:23], 11
	v_lshl_add_u64 v[28:29], v[2:3], 0, s[26:27]
	s_waitcnt vmcnt(3)
	v_cvt_pk_bf16_f32 v30, v12, v13
	v_cvt_pk_bf16_f32 v31, v14, v15
	global_store_dwordx2 v[28:29], v[30:31], off
	v_mul_f32_e32 v13, v13, v13
	v_mul_f32_e32 v15, v15, v15
	v_fmac_f32_e32 v13, v12, v12
	v_fmac_f32_e32 v15, v14, v14
	v_add_f32_e32 v12, v13, v15
	s_waitcnt vmcnt(3)
	v_cvt_pk_bf16_f32 v32, v16, v17
	v_cvt_pk_bf16_f32 v33, v18, v19
	global_store_dwordx2 v[28:29], v[32:33], off offset:512
	v_mul_f32_e32 v13, v17, v17
	v_mul_f32_e32 v14, v19, v19
	v_fmac_f32_e32 v13, v16, v16
	v_fmac_f32_e32 v14, v18, v18
	v_add_f32_e32 v13, v13, v14
	v_add_f32_e32 v12, v12, v13
	s_waitcnt vmcnt(3)
	v_cvt_pk_bf16_f32 v34, v20, v21
	v_cvt_pk_bf16_f32 v35, v22, v23
	global_store_dwordx2 v[28:29], v[34:35], off offset:1024
	v_mul_f32_e32 v13, v21, v21
	v_mul_f32_e32 v14, v23, v23
	v_fmac_f32_e32 v13, v20, v20
	v_fmac_f32_e32 v14, v22, v22
	v_add_f32_e32 v13, v13, v14
	v_add_f32_e32 v12, v12, v13
	s_waitcnt vmcnt(3)
	v_mul_f32_e32 v13, v25, v25
	v_mul_f32_e32 v14, v27, v27
	v_fmac_f32_e32 v13, v24, v24
	v_fmac_f32_e32 v14, v26, v26
	v_add_f32_e32 v13, v13, v14
	v_add_f32_e32 v12, v12, v13
	ds_bpermute_b32 v13, v6, v12
	v_cvt_pk_bf16_f32 v14, v24, v25
	v_cvt_pk_bf16_f32 v15, v26, v27
	global_store_dwordx2 v[28:29], v[14:15], off offset:1536
	s_waitcnt lgkmcnt(0)
	v_add_f32_e32 v12, v12, v13
	ds_bpermute_b32 v13, v7, v12
	s_waitcnt lgkmcnt(0)
	v_add_f32_e32 v12, v12, v13
	ds_bpermute_b32 v13, v8, v12
	s_waitcnt lgkmcnt(0)
	v_add_f32_e32 v12, v12, v13
	ds_bpermute_b32 v13, v9, v12
	s_waitcnt lgkmcnt(0)
	v_add_f32_e32 v12, v12, v13
	ds_bpermute_b32 v13, v10, v12
	s_waitcnt lgkmcnt(0)
	v_add_f32_e32 v12, v12, v13
	ds_bpermute_b32 v13, v11, v12
	s_and_saveexec_b64 s[24:25], s[6:7]
	s_cbranch_execz .LBB0_27
	s_lshl_b64 s[22:23], s[22:23], 6
	s_waitcnt lgkmcnt(0)
	v_add_f32_e32 v12, v12, v13
	v_lshl_add_u64 v[14:15], v[4:5], 0, s[22:23]
	v_cndmask_b32_e64 v12, 0, v12, s[8:9]
	global_store_dword v[14:15], v12, off
	s_branch .LBB0_27
